# speedup vs baseline: 1.0136x; 1.0136x over previous
.LBB0_389:
	s_cmp_gt_u32 s87, 30
	s_cbranch_scc1 .Lv0_c0
	s_waitcnt vmcnt(4)

.LBB0_395:
.Lfz1_c0:
	s_and_b32 s27, s86, 0xc000
	v_add_u32_e32 v241, s27, v233
	ds_read_b128 v[144:147], v241 offset:0
	v_xor_b32_e32 v240, 32, v241
	ds_read_b128 v[148:151], v240 offset:0
	v_xor_b32_e32 v239, 64, v241
	ds_read_b128 v[152:155], v239 offset:0
	v_xor_b32_e32 v0, 0x60, v241
	ds_read_b128 v[156:159], v0 offset:0
	s_waitcnt lgkmcnt(0)
	v_mfma_f32_32x32x16_bf16 v[212:227], v[144:147], v[176:179], 0
	v_mfma_f32_32x32x16_bf16 v[212:227], v[148:151], v[180:183], v[212:227]
	v_mfma_f32_32x32x16_bf16 v[212:227], v[152:155], v[184:187], v[212:227]
	v_mfma_f32_32x32x16_bf16 v[212:227], v[156:159], v[188:191], v[212:227]
	ds_read_b128 v[144:147], v241 offset:0x80
	ds_read_b128 v[148:151], v240 offset:0x80
	ds_read_b128 v[152:155], v239 offset:0x80
	ds_read_b128 v[156:159], v0 offset:0x80
	v_cmp_eq_f32_e32 vcc, 0, v238
	v_cmp_eq_f32_e64 s[10:11], 0, v237
	s_and_b64 s[0:1], vcc, s[10:11]
	s_cmp_eq_u64 s[0:1], exec
	s_waitcnt lgkmcnt(0)
	v_mfma_f32_32x32x16_bf16 v[160:175], v[144:147], v[192:195], 0
	v_mfma_f32_32x32x16_bf16 v[160:175], v[148:151], v[196:199], v[160:175]
	v_mfma_f32_32x32x16_bf16 v[160:175], v[152:155], v[200:203], v[160:175]
	v_mfma_f32_32x32x16_bf16 v[160:175], v[156:159], v[204:207], v[160:175]
	s_cbranch_scc0 .LBB0_397
	v_exp_f32_e32 v144, v212
	v_exp_f32_e32 v145, v213
	v_exp_f32_e32 v146, v214
	v_exp_f32_e32 v147, v215
	v_exp_f32_e32 v148, v216
	v_exp_f32_e32 v149, v217
	v_exp_f32_e32 v150, v218
	v_exp_f32_e32 v151, v219
	v_exp_f32_e32 v152, v220
	v_exp_f32_e32 v153, v221
	v_exp_f32_e32 v154, v222
	v_exp_f32_e32 v155, v223
	v_exp_f32_e32 v156, v224
	v_exp_f32_e32 v157, v225
	v_exp_f32_e32 v158, v226
	v_exp_f32_e32 v159, v227
	v_add_f32_e32 v252, v144, v145
	v_add_f32_e32 v253, v146, v147
	v_add_f32_e32 v254, v148, v149
	v_add_f32_e32 v255, v150, v151
	v_add_f32_e32 v252, v252, v152
	v_add_f32_e32 v253, v253, v153
	v_add_f32_e32 v254, v254, v154
	v_add_f32_e32 v255, v255, v155
	v_add_f32_e32 v252, v252, v156
	v_add_f32_e32 v253, v253, v157
	v_add_f32_e32 v254, v254, v158
	v_add_f32_e32 v255, v255, v159
	v_cvt_pk_bf16_f32 v216, v144, v145
	v_cvt_pk_bf16_f32 v217, v146, v147
	v_add_f32_e32 v252, v252, v253
	v_add_f32_e32 v254, v254, v255
	v_cvt_pk_bf16_f32 v218, v148, v149
	v_cvt_pk_bf16_f32 v219, v150, v151
	v_cvt_pk_bf16_f32 v224, v152, v153
	v_add_f32_e32 v252, v252, v254
	v_cvt_pk_bf16_f32 v225, v154, v155
	v_cvt_pk_bf16_f32 v226, v156, v157
	v_cvt_pk_bf16_f32 v227, v158, v159
	v_add_u32_e32 v253, 0xde801b54, v252
	v_cmp_gt_u32_e32 vcc, 0x3bff7543, v253
	s_cmp_lg_u64 vcc, exec
	s_cbranch_scc1 .LBB0_432
	v_add_f32_e32 v15, v15, v252
	v_exp_f32_e32 v144, v160
	v_exp_f32_e32 v145, v161
	v_exp_f32_e32 v146, v162
	v_exp_f32_e32 v147, v163
	v_exp_f32_e32 v148, v164
	v_exp_f32_e32 v149, v165
	v_exp_f32_e32 v150, v166
	v_exp_f32_e32 v151, v167
	v_exp_f32_e32 v152, v168
	v_exp_f32_e32 v153, v169
	v_exp_f32_e32 v154, v170
	v_exp_f32_e32 v155, v171
	v_exp_f32_e32 v156, v172
	v_exp_f32_e32 v157, v173
	v_exp_f32_e32 v158, v174
	v_exp_f32_e32 v159, v175
	v_add_f32_e32 v252, v144, v145
	v_add_f32_e32 v253, v146, v147
	v_add_f32_e32 v254, v148, v149
	v_add_f32_e32 v255, v150, v151
	v_add_f32_e32 v252, v252, v152
	v_add_f32_e32 v253, v253, v153
	v_add_f32_e32 v254, v254, v154
	v_add_f32_e32 v255, v255, v155
	v_add_f32_e32 v252, v252, v156
	v_add_f32_e32 v253, v253, v157
	v_add_f32_e32 v254, v254, v158
	v_add_f32_e32 v255, v255, v159
	v_cvt_pk_bf16_f32 v212, v144, v145
	v_cvt_pk_bf16_f32 v213, v146, v147
	v_add_f32_e32 v252, v252, v253
	v_add_f32_e32 v254, v254, v255
	v_cvt_pk_bf16_f32 v214, v148, v149
	v_cvt_pk_bf16_f32 v215, v150, v151
	v_cvt_pk_bf16_f32 v220, v152, v153
	v_add_f32_e32 v252, v252, v254
	v_cvt_pk_bf16_f32 v221, v154, v155
	v_cvt_pk_bf16_f32 v222, v156, v157
	v_cvt_pk_bf16_f32 v223, v158, v159
	v_add_u32_e32 v253, 0xde801b54, v252
	v_cmp_gt_u32_e32 vcc, 0x3bff7543, v253
	s_cmp_lg_u64 vcc, exec
	s_cbranch_scc1 .Lfzsb1_c0
	v_add_f32_e32 v14, v14, v252
.LBB0_413:
	v_add_u32_e32 v242, s27, v234
	ds_read_b64_tr_b16 v[160:161], v242 offset:0x0
	ds_read_b64_tr_b16 v[162:163], v242 offset:0x100
	ds_read_b64_tr_b16 v[164:165], v242 offset:0x1000
	ds_read_b64_tr_b16 v[166:167], v242 offset:0x1100
	s_waitcnt lgkmcnt(2)
	v_mfma_f32_32x32x16_bf16 v[128:143], v[216:219], v[160:163], v[128:143]
	ds_read_b64_tr_b16 v[168:169], v242 offset:0x200
	v_mfma_f32_32x32x16_bf16 v[96:111], v[212:215], v[160:163], v[96:111]
	ds_read_b64_tr_b16 v[170:171], v242 offset:0x300
	s_waitcnt lgkmcnt(2)
	v_mfma_f32_32x32x16_bf16 v[128:143], v[224:227], v[164:167], v[128:143]
	ds_read_b64_tr_b16 v[172:173], v242 offset:0x1200
	v_mfma_f32_32x32x16_bf16 v[96:111], v[220:223], v[164:167], v[96:111]
	ds_read_b64_tr_b16 v[174:175], v242 offset:0x1300
	s_waitcnt lgkmcnt(2)
	v_mfma_f32_32x32x16_bf16 v[112:127], v[216:219], v[168:171], v[112:127]
	ds_read_b64_tr_b16 v[160:161], v242 offset:0x400
	v_mfma_f32_32x32x16_bf16 v[80:95], v[212:215], v[168:171], v[80:95]
	ds_read_b64_tr_b16 v[162:163], v242 offset:0x500
	s_waitcnt lgkmcnt(2)
	v_mfma_f32_32x32x16_bf16 v[112:127], v[224:227], v[172:175], v[112:127]
	ds_read_b64_tr_b16 v[164:165], v242 offset:0x1400
	v_mfma_f32_32x32x16_bf16 v[80:95], v[220:223], v[172:175], v[80:95]
	ds_read_b64_tr_b16 v[166:167], v242 offset:0x1500
	ds_read_b128 v[144:147], v241 offset:0x2000
	ds_read_b128 v[148:151], v240 offset:0x2000
	ds_read_b128 v[152:155], v239 offset:0x2000
	ds_read_b128 v[156:159], v0 offset:0x2000
	s_waitcnt lgkmcnt(6)
	v_mfma_f32_32x32x16_bf16 v[64:79], v[216:219], v[160:163], v[64:79]
	ds_read_b64_tr_b16 v[168:169], v242 offset:0x600
	v_mfma_f32_32x32x16_bf16 v[32:47], v[212:215], v[160:163], v[32:47]
	ds_read_b64_tr_b16 v[170:171], v242 offset:0x700
	s_waitcnt lgkmcnt(6)
	v_mfma_f32_32x32x16_bf16 v[64:79], v[224:227], v[164:167], v[64:79]
	ds_read_b64_tr_b16 v[172:173], v242 offset:0x1600
	v_mfma_f32_32x32x16_bf16 v[32:47], v[220:223], v[164:167], v[32:47]
	ds_read_b64_tr_b16 v[174:175], v242 offset:0x1700
	s_waitcnt lgkmcnt(2)
	v_mfma_f32_32x32x16_bf16 v[48:63], v[216:219], v[168:171], v[48:63]
	v_mfma_f32_32x32x16_bf16 v[16:31], v[212:215], v[168:171], v[16:31]
	s_waitcnt lgkmcnt(0)
	v_mfma_f32_32x32x16_bf16 v[48:63], v[224:227], v[172:175], v[48:63]
	v_mfma_f32_32x32x16_bf16 v[16:31], v[220:223], v[172:175], v[16:31]
	s_waitcnt lgkmcnt(0)
	v_mfma_f32_32x32x16_bf16 v[212:227], v[144:147], v[176:179], 0
	v_mfma_f32_32x32x16_bf16 v[212:227], v[148:151], v[180:183], v[212:227]
	v_mfma_f32_32x32x16_bf16 v[212:227], v[152:155], v[184:187], v[212:227]
	v_mfma_f32_32x32x16_bf16 v[212:227], v[156:159], v[188:191], v[212:227]
	ds_read_b128 v[144:147], v241 offset:0x2080
	ds_read_b128 v[148:151], v240 offset:0x2080
	ds_read_b128 v[152:155], v239 offset:0x2080
	ds_read_b128 v[156:159], v0 offset:0x2080
	v_cmp_eq_f32_e32 vcc, 0, v238
	v_cmp_eq_f32_e64 s[10:11], 0, v237
	s_and_b64 s[0:1], vcc, s[10:11]
	s_cmp_eq_u64 s[0:1], exec
	s_waitcnt lgkmcnt(0)
	v_mfma_f32_32x32x16_bf16 v[160:175], v[144:147], v[192:195], 0
	v_mfma_f32_32x32x16_bf16 v[160:175], v[148:151], v[196:199], v[160:175]
	v_mfma_f32_32x32x16_bf16 v[160:175], v[152:155], v[200:203], v[160:175]
	v_mfma_f32_32x32x16_bf16 v[160:175], v[156:159], v[204:207], v[160:175]
	s_cbranch_scc0 .Lfz2o_c0
	v_exp_f32_e32 v144, v212
	v_exp_f32_e32 v145, v213
	v_exp_f32_e32 v146, v214
	v_exp_f32_e32 v147, v215
	v_exp_f32_e32 v148, v216
	v_exp_f32_e32 v149, v217
	v_exp_f32_e32 v150, v218
	v_exp_f32_e32 v151, v219
	v_exp_f32_e32 v152, v220
	v_exp_f32_e32 v153, v221
	v_exp_f32_e32 v154, v222
	v_exp_f32_e32 v155, v223
	v_exp_f32_e32 v156, v224
	v_exp_f32_e32 v157, v225
	v_exp_f32_e32 v158, v226
	v_exp_f32_e32 v159, v227
	v_add_f32_e32 v252, v144, v145
	v_add_f32_e32 v253, v146, v147
	v_add_f32_e32 v254, v148, v149
	v_add_f32_e32 v255, v150, v151
	v_add_f32_e32 v252, v252, v152
	v_add_f32_e32 v253, v253, v153
	v_add_f32_e32 v254, v254, v154
	v_add_f32_e32 v255, v255, v155
	v_add_f32_e32 v252, v252, v156
	v_add_f32_e32 v253, v253, v157
	v_add_f32_e32 v254, v254, v158
	v_add_f32_e32 v255, v255, v159
	v_cvt_pk_bf16_f32 v6, v144, v145
	v_cvt_pk_bf16_f32 v7, v146, v147
	v_add_f32_e32 v252, v252, v253
	v_add_f32_e32 v254, v254, v255
	v_cvt_pk_bf16_f32 v8, v148, v149
	v_cvt_pk_bf16_f32 v9, v150, v151
	v_cvt_pk_bf16_f32 v208, v152, v153
	v_add_f32_e32 v252, v252, v254
	v_cvt_pk_bf16_f32 v209, v154, v155
	v_cvt_pk_bf16_f32 v210, v156, v157
	v_cvt_pk_bf16_f32 v211, v158, v159
	v_add_u32_e32 v253, 0xde801b54, v252
	v_cmp_gt_u32_e32 vcc, 0x3bff7543, v253
	s_cmp_lg_u64 vcc, exec
	s_cbranch_scc1 .LBB0_444
	v_add_f32_e32 v15, v15, v252
	v_exp_f32_e32 v144, v160
	v_exp_f32_e32 v145, v161
	v_exp_f32_e32 v146, v162
	v_exp_f32_e32 v147, v163
	v_exp_f32_e32 v148, v164
	v_exp_f32_e32 v149, v165
	v_exp_f32_e32 v150, v166
	v_exp_f32_e32 v151, v167
	v_exp_f32_e32 v152, v168
	v_exp_f32_e32 v153, v169
	v_exp_f32_e32 v154, v170
	v_exp_f32_e32 v155, v171
	v_exp_f32_e32 v156, v172
	v_exp_f32_e32 v157, v173
	v_exp_f32_e32 v158, v174
	v_exp_f32_e32 v159, v175
	v_add_f32_e32 v252, v144, v145
	v_add_f32_e32 v253, v146, v147
	v_add_f32_e32 v254, v148, v149
	v_add_f32_e32 v255, v150, v151
	v_add_f32_e32 v252, v252, v152
	v_add_f32_e32 v253, v253, v153
	v_add_f32_e32 v254, v254, v154
	v_add_f32_e32 v255, v255, v155
	v_add_f32_e32 v252, v252, v156
	v_add_f32_e32 v253, v253, v157
	v_add_f32_e32 v254, v254, v158
	v_add_f32_e32 v255, v255, v159
	v_cvt_pk_bf16_f32 v2, v144, v145
	v_cvt_pk_bf16_f32 v3, v146, v147
	v_add_f32_e32 v252, v252, v253
	v_add_f32_e32 v254, v254, v255
	v_cvt_pk_bf16_f32 v4, v148, v149
	v_cvt_pk_bf16_f32 v5, v150, v151
	v_cvt_pk_bf16_f32 v10, v152, v153
	v_add_f32_e32 v252, v252, v254
	v_cvt_pk_bf16_f32 v11, v154, v155
	v_cvt_pk_bf16_f32 v12, v156, v157
	v_cvt_pk_bf16_f32 v13, v158, v159
	v_add_u32_e32 v253, 0xde801b54, v252
	v_cmp_gt_u32_e32 vcc, 0x3bff7543, v253
	s_cmp_lg_u64 vcc, exec
	s_cbranch_scc1 .Lfzsb2_c0
	v_add_f32_e32 v14, v14, v252

.Lv0_c0:
	s_waitcnt vmcnt(0)
	s_branch .Lbar_c0

.LBB0_410:
	s_and_saveexec_b64 s[0:1], s[8:9]
	ds_write2_b32 v235, v242, v243 offset1:32
	s_or_b64 exec, exec, s[0:1]
	s_waitcnt lgkmcnt(0)
	ds_read_b128 v[160:163], v236
	ds_read_b128 v[164:167], v236 offset:32
	ds_read_b128 v[168:171], v236 offset:64
	ds_read_b128 v[172:175], v236 offset:96
	ds_read_b128 v[144:147], v236 offset:128
	ds_read_b128 v[148:151], v236 offset:160
	ds_read_b128 v[152:155], v236 offset:192
	ds_read_b128 v[156:159], v236 offset:224
	s_waitcnt lgkmcnt(0)
	v_pk_mul_f32 v[142:143], v[142:143], v[174:175]
	v_pk_mul_f32 v[138:139], v[138:139], v[170:171]
	v_pk_mul_f32 v[134:135], v[134:135], v[166:167]
	v_pk_mul_f32 v[130:131], v[130:131], v[162:163]
	v_pk_mul_f32 v[140:141], v[140:141], v[172:173]
	v_pk_mul_f32 v[136:137], v[136:137], v[168:169]
	v_pk_mul_f32 v[132:133], v[132:133], v[164:165]
	v_pk_mul_f32 v[128:129], v[128:129], v[160:161]
	v_pk_mul_f32 v[126:127], v[126:127], v[174:175]
	v_pk_mul_f32 v[122:123], v[122:123], v[170:171]
	v_pk_mul_f32 v[118:119], v[118:119], v[166:167]
	v_pk_mul_f32 v[114:115], v[114:115], v[162:163]
	v_pk_mul_f32 v[124:125], v[124:125], v[172:173]
	v_pk_mul_f32 v[120:121], v[120:121], v[168:169]
	v_pk_mul_f32 v[116:117], v[116:117], v[164:165]
	v_pk_mul_f32 v[112:113], v[112:113], v[160:161]
	v_pk_mul_f32 v[78:79], v[78:79], v[174:175]
	v_pk_mul_f32 v[74:75], v[74:75], v[170:171]
	v_pk_mul_f32 v[70:71], v[70:71], v[166:167]
	v_pk_mul_f32 v[66:67], v[66:67], v[162:163]
	v_pk_mul_f32 v[76:77], v[76:77], v[172:173]
	v_pk_mul_f32 v[72:73], v[72:73], v[168:169]
	v_pk_mul_f32 v[68:69], v[68:69], v[164:165]
	v_pk_mul_f32 v[64:65], v[64:65], v[160:161]
	v_pk_mul_f32 v[62:63], v[62:63], v[174:175]
	v_pk_mul_f32 v[58:59], v[58:59], v[170:171]
	v_pk_mul_f32 v[54:55], v[54:55], v[166:167]
	v_pk_mul_f32 v[50:51], v[50:51], v[162:163]
	v_pk_mul_f32 v[60:61], v[60:61], v[172:173]
	v_pk_mul_f32 v[56:57], v[56:57], v[168:169]
	v_pk_mul_f32 v[52:53], v[52:53], v[164:165]
	v_pk_mul_f32 v[48:49], v[48:49], v[160:161]
	v_pk_mul_f32 v[110:111], v[110:111], v[158:159]
	v_pk_mul_f32 v[106:107], v[106:107], v[154:155]
	v_pk_mul_f32 v[102:103], v[102:103], v[150:151]
	v_pk_mul_f32 v[98:99], v[98:99], v[146:147]
	v_pk_mul_f32 v[108:109], v[108:109], v[156:157]
	v_pk_mul_f32 v[104:105], v[104:105], v[152:153]
	v_pk_mul_f32 v[100:101], v[100:101], v[148:149]
	v_pk_mul_f32 v[96:97], v[96:97], v[144:145]
	v_pk_mul_f32 v[94:95], v[94:95], v[158:159]
	v_pk_mul_f32 v[90:91], v[90:91], v[154:155]
	v_pk_mul_f32 v[86:87], v[86:87], v[150:151]
	v_pk_mul_f32 v[82:83], v[82:83], v[146:147]
	v_pk_mul_f32 v[92:93], v[92:93], v[156:157]
	v_pk_mul_f32 v[88:89], v[88:89], v[152:153]
	v_pk_mul_f32 v[84:85], v[84:85], v[148:149]
	v_pk_mul_f32 v[80:81], v[80:81], v[144:145]
	v_pk_mul_f32 v[46:47], v[46:47], v[158:159]
	v_pk_mul_f32 v[42:43], v[42:43], v[154:155]
	v_pk_mul_f32 v[38:39], v[38:39], v[150:151]
	v_pk_mul_f32 v[34:35], v[34:35], v[146:147]
	v_pk_mul_f32 v[44:45], v[44:45], v[156:157]
	v_pk_mul_f32 v[40:41], v[40:41], v[152:153]
	v_pk_mul_f32 v[36:37], v[36:37], v[148:149]
	v_pk_mul_f32 v[32:33], v[32:33], v[144:145]
	v_pk_mul_f32 v[30:31], v[30:31], v[158:159]
	v_pk_mul_f32 v[26:27], v[26:27], v[154:155]
	v_pk_mul_f32 v[22:23], v[22:23], v[150:151]
	v_pk_mul_f32 v[18:19], v[18:19], v[146:147]
	v_pk_mul_f32 v[28:29], v[28:29], v[156:157]
	v_pk_mul_f32 v[24:25], v[24:25], v[152:153]
	v_pk_mul_f32 v[20:21], v[20:21], v[148:149]
	v_pk_mul_f32 v[16:17], v[16:17], v[144:145]
	s_branch .LBB0_413

.LBB0_426:
	s_and_saveexec_b64 s[0:1], s[8:9]
	ds_write2_b32 v235, v243, v244 offset1:32
	s_or_b64 exec, exec, s[0:1]
	s_waitcnt lgkmcnt(0)
	ds_read_b128 v[160:163], v236
	ds_read_b128 v[164:167], v236 offset:32
	ds_read_b128 v[168:171], v236 offset:64
	ds_read_b128 v[172:175], v236 offset:96
	ds_read_b128 v[144:147], v236 offset:128
	ds_read_b128 v[148:151], v236 offset:160
	ds_read_b128 v[152:155], v236 offset:192
	ds_read_b128 v[156:159], v236 offset:224
	s_waitcnt lgkmcnt(0)
	v_pk_mul_f32 v[142:143], v[142:143], v[174:175]
	v_pk_mul_f32 v[138:139], v[138:139], v[170:171]
	v_pk_mul_f32 v[134:135], v[134:135], v[166:167]
	v_pk_mul_f32 v[130:131], v[130:131], v[162:163]
	v_pk_mul_f32 v[140:141], v[140:141], v[172:173]
	v_pk_mul_f32 v[136:137], v[136:137], v[168:169]
	v_pk_mul_f32 v[132:133], v[132:133], v[164:165]
	v_pk_mul_f32 v[128:129], v[128:129], v[160:161]
	v_pk_mul_f32 v[126:127], v[126:127], v[174:175]
	v_pk_mul_f32 v[122:123], v[122:123], v[170:171]
	v_pk_mul_f32 v[118:119], v[118:119], v[166:167]
	v_pk_mul_f32 v[114:115], v[114:115], v[162:163]
	v_pk_mul_f32 v[124:125], v[124:125], v[172:173]
	v_pk_mul_f32 v[120:121], v[120:121], v[168:169]
	v_pk_mul_f32 v[116:117], v[116:117], v[164:165]
	v_pk_mul_f32 v[112:113], v[112:113], v[160:161]
	v_pk_mul_f32 v[78:79], v[78:79], v[174:175]
	v_pk_mul_f32 v[74:75], v[74:75], v[170:171]
	v_pk_mul_f32 v[70:71], v[70:71], v[166:167]
	v_pk_mul_f32 v[66:67], v[66:67], v[162:163]
	v_pk_mul_f32 v[76:77], v[76:77], v[172:173]
	v_pk_mul_f32 v[72:73], v[72:73], v[168:169]
	v_pk_mul_f32 v[68:69], v[68:69], v[164:165]
	v_pk_mul_f32 v[64:65], v[64:65], v[160:161]
	v_pk_mul_f32 v[62:63], v[62:63], v[174:175]
	v_pk_mul_f32 v[58:59], v[58:59], v[170:171]
	v_pk_mul_f32 v[54:55], v[54:55], v[166:167]
	v_pk_mul_f32 v[50:51], v[50:51], v[162:163]
	v_pk_mul_f32 v[60:61], v[60:61], v[172:173]
	v_pk_mul_f32 v[56:57], v[56:57], v[168:169]
	v_pk_mul_f32 v[52:53], v[52:53], v[164:165]
	v_pk_mul_f32 v[48:49], v[48:49], v[160:161]
	v_pk_mul_f32 v[110:111], v[110:111], v[158:159]
	v_pk_mul_f32 v[106:107], v[106:107], v[154:155]
	v_pk_mul_f32 v[102:103], v[102:103], v[150:151]
	v_pk_mul_f32 v[98:99], v[98:99], v[146:147]
	v_pk_mul_f32 v[108:109], v[108:109], v[156:157]
	v_pk_mul_f32 v[104:105], v[104:105], v[152:153]
	v_pk_mul_f32 v[100:101], v[100:101], v[148:149]
	v_pk_mul_f32 v[96:97], v[96:97], v[144:145]
	v_pk_mul_f32 v[94:95], v[94:95], v[158:159]
	v_pk_mul_f32 v[90:91], v[90:91], v[154:155]
	v_pk_mul_f32 v[86:87], v[86:87], v[150:151]
	v_pk_mul_f32 v[82:83], v[82:83], v[146:147]
	v_pk_mul_f32 v[92:93], v[92:93], v[156:157]
	v_pk_mul_f32 v[88:89], v[88:89], v[152:153]
	v_pk_mul_f32 v[84:85], v[84:85], v[148:149]
	v_pk_mul_f32 v[80:81], v[80:81], v[144:145]
	v_pk_mul_f32 v[46:47], v[46:47], v[158:159]
	v_pk_mul_f32 v[42:43], v[42:43], v[154:155]
	v_pk_mul_f32 v[38:39], v[38:39], v[150:151]
	v_pk_mul_f32 v[34:35], v[34:35], v[146:147]
	v_pk_mul_f32 v[44:45], v[44:45], v[156:157]
	v_pk_mul_f32 v[40:41], v[40:41], v[152:153]
	v_pk_mul_f32 v[36:37], v[36:37], v[148:149]
	v_pk_mul_f32 v[32:33], v[32:33], v[144:145]
	v_pk_mul_f32 v[30:31], v[30:31], v[158:159]
	v_pk_mul_f32 v[26:27], v[26:27], v[154:155]
	v_pk_mul_f32 v[22:23], v[22:23], v[150:151]
	v_pk_mul_f32 v[18:19], v[18:19], v[146:147]
	v_pk_mul_f32 v[28:29], v[28:29], v[156:157]
	v_pk_mul_f32 v[24:25], v[24:25], v[152:153]
	v_pk_mul_f32 v[20:21], v[20:21], v[148:149]
	v_pk_mul_f32 v[16:17], v[16:17], v[144:145]
	s_branch .LBB0_429

.LBB0_1243:
	s_cmpk_gt_u32 s79, 0xfe
	s_cbranch_scc1 .Lv0_c1
	s_waitcnt vmcnt(4)

.LBB0_1249:
.Lfz1_c1:
	s_and_b32 s27, s77, 0xc000
	v_add_u32_e32 v241, s27, v233
	ds_read_b128 v[144:147], v241 offset:0
	v_xor_b32_e32 v240, 32, v241
	ds_read_b128 v[148:151], v240 offset:0
	v_xor_b32_e32 v239, 64, v241
	ds_read_b128 v[152:155], v239 offset:0
	v_xor_b32_e32 v0, 0x60, v241
	ds_read_b128 v[156:159], v0 offset:0
	s_waitcnt lgkmcnt(0)
	v_mfma_f32_32x32x16_bf16 v[212:227], v[144:147], v[176:179], 0
	v_mfma_f32_32x32x16_bf16 v[212:227], v[148:151], v[180:183], v[212:227]
	v_mfma_f32_32x32x16_bf16 v[212:227], v[152:155], v[184:187], v[212:227]
	v_mfma_f32_32x32x16_bf16 v[212:227], v[156:159], v[188:191], v[212:227]
	ds_read_b128 v[144:147], v241 offset:0x80
	ds_read_b128 v[148:151], v240 offset:0x80
	ds_read_b128 v[152:155], v239 offset:0x80
	ds_read_b128 v[156:159], v0 offset:0x80
	v_cmp_eq_f32_e32 vcc, 0, v238
	v_cmp_eq_f32_e64 s[10:11], 0, v237
	s_and_b64 s[0:1], vcc, s[10:11]
	s_cmp_eq_u64 s[0:1], exec
	s_waitcnt lgkmcnt(0)
	v_mfma_f32_32x32x16_bf16 v[160:175], v[144:147], v[192:195], 0
	v_mfma_f32_32x32x16_bf16 v[160:175], v[148:151], v[196:199], v[160:175]
	v_mfma_f32_32x32x16_bf16 v[160:175], v[152:155], v[200:203], v[160:175]
	v_mfma_f32_32x32x16_bf16 v[160:175], v[156:159], v[204:207], v[160:175]
	s_cbranch_scc0 .LBB0_1251
	v_exp_f32_e32 v144, v212
	v_exp_f32_e32 v145, v213
	v_exp_f32_e32 v146, v214
	v_exp_f32_e32 v147, v215
	v_exp_f32_e32 v148, v216
	v_exp_f32_e32 v149, v217
	v_exp_f32_e32 v150, v218
	v_exp_f32_e32 v151, v219
	v_exp_f32_e32 v152, v220
	v_exp_f32_e32 v153, v221
	v_exp_f32_e32 v154, v222
	v_exp_f32_e32 v155, v223
	v_exp_f32_e32 v156, v224
	v_exp_f32_e32 v157, v225
	v_exp_f32_e32 v158, v226
	v_exp_f32_e32 v159, v227
	v_add_f32_e32 v252, v144, v145
	v_add_f32_e32 v253, v146, v147
	v_add_f32_e32 v254, v148, v149
	v_add_f32_e32 v255, v150, v151
	v_add_f32_e32 v252, v252, v152
	v_add_f32_e32 v253, v253, v153
	v_add_f32_e32 v254, v254, v154
	v_add_f32_e32 v255, v255, v155
	v_add_f32_e32 v252, v252, v156
	v_add_f32_e32 v253, v253, v157
	v_add_f32_e32 v254, v254, v158
	v_add_f32_e32 v255, v255, v159
	v_cvt_pk_bf16_f32 v216, v144, v145
	v_cvt_pk_bf16_f32 v217, v146, v147
	v_add_f32_e32 v252, v252, v253
	v_add_f32_e32 v254, v254, v255
	v_cvt_pk_bf16_f32 v218, v148, v149
	v_cvt_pk_bf16_f32 v219, v150, v151
	v_cvt_pk_bf16_f32 v224, v152, v153
	v_add_f32_e32 v252, v252, v254
	v_cvt_pk_bf16_f32 v225, v154, v155
	v_cvt_pk_bf16_f32 v226, v156, v157
	v_cvt_pk_bf16_f32 v227, v158, v159
	v_add_u32_e32 v253, 0xde801b54, v252
	v_cmp_gt_u32_e32 vcc, 0x3bff7543, v253
	s_cmp_lg_u64 vcc, exec
	s_cbranch_scc1 .LBB0_1286
	v_add_f32_e32 v15, v15, v252
	v_exp_f32_e32 v144, v160
	v_exp_f32_e32 v145, v161
	v_exp_f32_e32 v146, v162
	v_exp_f32_e32 v147, v163
	v_exp_f32_e32 v148, v164
	v_exp_f32_e32 v149, v165
	v_exp_f32_e32 v150, v166
	v_exp_f32_e32 v151, v167
	v_exp_f32_e32 v152, v168
	v_exp_f32_e32 v153, v169
	v_exp_f32_e32 v154, v170
	v_exp_f32_e32 v155, v171
	v_exp_f32_e32 v156, v172
	v_exp_f32_e32 v157, v173
	v_exp_f32_e32 v158, v174
	v_exp_f32_e32 v159, v175
	v_add_f32_e32 v252, v144, v145
	v_add_f32_e32 v253, v146, v147
	v_add_f32_e32 v254, v148, v149
	v_add_f32_e32 v255, v150, v151
	v_add_f32_e32 v252, v252, v152
	v_add_f32_e32 v253, v253, v153
	v_add_f32_e32 v254, v254, v154
	v_add_f32_e32 v255, v255, v155
	v_add_f32_e32 v252, v252, v156
	v_add_f32_e32 v253, v253, v157
	v_add_f32_e32 v254, v254, v158
	v_add_f32_e32 v255, v255, v159
	v_cvt_pk_bf16_f32 v212, v144, v145
	v_cvt_pk_bf16_f32 v213, v146, v147
	v_add_f32_e32 v252, v252, v253
	v_add_f32_e32 v254, v254, v255
	v_cvt_pk_bf16_f32 v214, v148, v149
	v_cvt_pk_bf16_f32 v215, v150, v151
	v_cvt_pk_bf16_f32 v220, v152, v153
	v_add_f32_e32 v252, v252, v254
	v_cvt_pk_bf16_f32 v221, v154, v155
	v_cvt_pk_bf16_f32 v222, v156, v157
	v_cvt_pk_bf16_f32 v223, v158, v159
	v_add_u32_e32 v253, 0xde801b54, v252
	v_cmp_gt_u32_e32 vcc, 0x3bff7543, v253
	s_cmp_lg_u64 vcc, exec
	s_cbranch_scc1 .Lfzsb1_c1
	v_add_f32_e32 v14, v14, v252
.LBB0_1267:
	v_add_u32_e32 v242, s27, v234
	ds_read_b64_tr_b16 v[160:161], v242 offset:0x0
	ds_read_b64_tr_b16 v[162:163], v242 offset:0x100
	ds_read_b64_tr_b16 v[164:165], v242 offset:0x1000
	ds_read_b64_tr_b16 v[166:167], v242 offset:0x1100
	s_waitcnt lgkmcnt(2)
	v_mfma_f32_32x32x16_bf16 v[128:143], v[216:219], v[160:163], v[128:143]
	ds_read_b64_tr_b16 v[168:169], v242 offset:0x200
	v_mfma_f32_32x32x16_bf16 v[96:111], v[212:215], v[160:163], v[96:111]
	ds_read_b64_tr_b16 v[170:171], v242 offset:0x300
	s_waitcnt lgkmcnt(2)
	v_mfma_f32_32x32x16_bf16 v[128:143], v[224:227], v[164:167], v[128:143]
	ds_read_b64_tr_b16 v[172:173], v242 offset:0x1200
	v_mfma_f32_32x32x16_bf16 v[96:111], v[220:223], v[164:167], v[96:111]
	ds_read_b64_tr_b16 v[174:175], v242 offset:0x1300
	s_waitcnt lgkmcnt(2)
	v_mfma_f32_32x32x16_bf16 v[112:127], v[216:219], v[168:171], v[112:127]
	ds_read_b64_tr_b16 v[160:161], v242 offset:0x400
	v_mfma_f32_32x32x16_bf16 v[80:95], v[212:215], v[168:171], v[80:95]
	ds_read_b64_tr_b16 v[162:163], v242 offset:0x500
	s_waitcnt lgkmcnt(2)
	v_mfma_f32_32x32x16_bf16 v[112:127], v[224:227], v[172:175], v[112:127]
	ds_read_b64_tr_b16 v[164:165], v242 offset:0x1400
	v_mfma_f32_32x32x16_bf16 v[80:95], v[220:223], v[172:175], v[80:95]
	ds_read_b64_tr_b16 v[166:167], v242 offset:0x1500
	ds_read_b128 v[144:147], v241 offset:0x2000
	ds_read_b128 v[148:151], v240 offset:0x2000
	ds_read_b128 v[152:155], v239 offset:0x2000
	ds_read_b128 v[156:159], v0 offset:0x2000
	s_waitcnt lgkmcnt(6)
	v_mfma_f32_32x32x16_bf16 v[64:79], v[216:219], v[160:163], v[64:79]
	ds_read_b64_tr_b16 v[168:169], v242 offset:0x600
	v_mfma_f32_32x32x16_bf16 v[48:63], v[212:215], v[160:163], v[48:63]
	ds_read_b64_tr_b16 v[170:171], v242 offset:0x700
	s_waitcnt lgkmcnt(6)
	v_mfma_f32_32x32x16_bf16 v[64:79], v[224:227], v[164:167], v[64:79]
	ds_read_b64_tr_b16 v[172:173], v242 offset:0x1600
	v_mfma_f32_32x32x16_bf16 v[48:63], v[220:223], v[164:167], v[48:63]
	ds_read_b64_tr_b16 v[174:175], v242 offset:0x1700
	s_waitcnt lgkmcnt(2)
	v_mfma_f32_32x32x16_bf16 v[32:47], v[216:219], v[168:171], v[32:47]
	v_mfma_f32_32x32x16_bf16 v[16:31], v[212:215], v[168:171], v[16:31]
	s_waitcnt lgkmcnt(0)
	v_mfma_f32_32x32x16_bf16 v[32:47], v[224:227], v[172:175], v[32:47]
	v_mfma_f32_32x32x16_bf16 v[16:31], v[220:223], v[172:175], v[16:31]
	s_waitcnt lgkmcnt(0)
	v_mfma_f32_32x32x16_bf16 v[212:227], v[144:147], v[176:179], 0
	v_mfma_f32_32x32x16_bf16 v[212:227], v[148:151], v[180:183], v[212:227]
	v_mfma_f32_32x32x16_bf16 v[212:227], v[152:155], v[184:187], v[212:227]
	v_mfma_f32_32x32x16_bf16 v[212:227], v[156:159], v[188:191], v[212:227]
	ds_read_b128 v[144:147], v241 offset:0x2080
	ds_read_b128 v[148:151], v240 offset:0x2080
	ds_read_b128 v[152:155], v239 offset:0x2080
	ds_read_b128 v[156:159], v0 offset:0x2080
	v_cmp_eq_f32_e32 vcc, 0, v238
	v_cmp_eq_f32_e64 s[10:11], 0, v237
	s_and_b64 s[0:1], vcc, s[10:11]
	s_cmp_eq_u64 s[0:1], exec
	s_waitcnt lgkmcnt(0)
	v_mfma_f32_32x32x16_bf16 v[160:175], v[144:147], v[192:195], 0
	v_mfma_f32_32x32x16_bf16 v[160:175], v[148:151], v[196:199], v[160:175]
	v_mfma_f32_32x32x16_bf16 v[160:175], v[152:155], v[200:203], v[160:175]
	v_mfma_f32_32x32x16_bf16 v[160:175], v[156:159], v[204:207], v[160:175]
	s_cbranch_scc0 .Lfz2o_c1
	v_exp_f32_e32 v144, v212
	v_exp_f32_e32 v145, v213
	v_exp_f32_e32 v146, v214
	v_exp_f32_e32 v147, v215
	v_exp_f32_e32 v148, v216
	v_exp_f32_e32 v149, v217
	v_exp_f32_e32 v150, v218
	v_exp_f32_e32 v151, v219
	v_exp_f32_e32 v152, v220
	v_exp_f32_e32 v153, v221
	v_exp_f32_e32 v154, v222
	v_exp_f32_e32 v155, v223
	v_exp_f32_e32 v156, v224
	v_exp_f32_e32 v157, v225
	v_exp_f32_e32 v158, v226
	v_exp_f32_e32 v159, v227
	v_add_f32_e32 v252, v144, v145
	v_add_f32_e32 v253, v146, v147
	v_add_f32_e32 v254, v148, v149
	v_add_f32_e32 v255, v150, v151
	v_add_f32_e32 v252, v252, v152
	v_add_f32_e32 v253, v253, v153
	v_add_f32_e32 v254, v254, v154
	v_add_f32_e32 v255, v255, v155
	v_add_f32_e32 v252, v252, v156
	v_add_f32_e32 v253, v253, v157
	v_add_f32_e32 v254, v254, v158
	v_add_f32_e32 v255, v255, v159
	v_cvt_pk_bf16_f32 v6, v144, v145
	v_cvt_pk_bf16_f32 v7, v146, v147
	v_add_f32_e32 v252, v252, v253
	v_add_f32_e32 v254, v254, v255
	v_cvt_pk_bf16_f32 v8, v148, v149
	v_cvt_pk_bf16_f32 v9, v150, v151
	v_cvt_pk_bf16_f32 v208, v152, v153
	v_add_f32_e32 v252, v252, v254
	v_cvt_pk_bf16_f32 v209, v154, v155
	v_cvt_pk_bf16_f32 v210, v156, v157
	v_cvt_pk_bf16_f32 v211, v158, v159
	v_add_u32_e32 v253, 0xde801b54, v252
	v_cmp_gt_u32_e32 vcc, 0x3bff7543, v253
	s_cmp_lg_u64 vcc, exec
	s_cbranch_scc1 .LBB0_1298
	v_add_f32_e32 v15, v15, v252
	v_exp_f32_e32 v144, v160
	v_exp_f32_e32 v145, v161
	v_exp_f32_e32 v146, v162
	v_exp_f32_e32 v147, v163
	v_exp_f32_e32 v148, v164
	v_exp_f32_e32 v149, v165
	v_exp_f32_e32 v150, v166
	v_exp_f32_e32 v151, v167
	v_exp_f32_e32 v152, v168
	v_exp_f32_e32 v153, v169
	v_exp_f32_e32 v154, v170
	v_exp_f32_e32 v155, v171
	v_exp_f32_e32 v156, v172
	v_exp_f32_e32 v157, v173
	v_exp_f32_e32 v158, v174
	v_exp_f32_e32 v159, v175
	v_add_f32_e32 v252, v144, v145
	v_add_f32_e32 v253, v146, v147
	v_add_f32_e32 v254, v148, v149
	v_add_f32_e32 v255, v150, v151
	v_add_f32_e32 v252, v252, v152
	v_add_f32_e32 v253, v253, v153
	v_add_f32_e32 v254, v254, v154
	v_add_f32_e32 v255, v255, v155
	v_add_f32_e32 v252, v252, v156
	v_add_f32_e32 v253, v253, v157
	v_add_f32_e32 v254, v254, v158
	v_add_f32_e32 v255, v255, v159
	v_cvt_pk_bf16_f32 v2, v144, v145
	v_cvt_pk_bf16_f32 v3, v146, v147
	v_add_f32_e32 v252, v252, v253
	v_add_f32_e32 v254, v254, v255
	v_cvt_pk_bf16_f32 v4, v148, v149
	v_cvt_pk_bf16_f32 v5, v150, v151
	v_cvt_pk_bf16_f32 v10, v152, v153
	v_add_f32_e32 v252, v252, v254
	v_cvt_pk_bf16_f32 v11, v154, v155
	v_cvt_pk_bf16_f32 v12, v156, v157
	v_cvt_pk_bf16_f32 v13, v158, v159
	v_add_u32_e32 v253, 0xde801b54, v252
	v_cmp_gt_u32_e32 vcc, 0x3bff7543, v253
	s_cmp_lg_u64 vcc, exec
	s_cbranch_scc1 .Lfzsb2_c1
	v_add_f32_e32 v14, v14, v252

.LBB0_1264:
	s_and_saveexec_b64 s[0:1], s[8:9]
	ds_write2_b32 v235, v242, v243 offset1:32
	s_or_b64 exec, exec, s[0:1]
	s_waitcnt lgkmcnt(0)
	ds_read_b128 v[160:163], v236
	ds_read_b128 v[164:167], v236 offset:32
	ds_read_b128 v[168:171], v236 offset:64
	ds_read_b128 v[172:175], v236 offset:96
	ds_read_b128 v[144:147], v236 offset:128
	ds_read_b128 v[148:151], v236 offset:160
	ds_read_b128 v[152:155], v236 offset:192
	ds_read_b128 v[156:159], v236 offset:224
	s_waitcnt lgkmcnt(0)
	v_pk_mul_f32 v[142:143], v[142:143], v[174:175]
	v_pk_mul_f32 v[138:139], v[138:139], v[170:171]
	v_pk_mul_f32 v[134:135], v[134:135], v[166:167]
	v_pk_mul_f32 v[130:131], v[130:131], v[162:163]
	v_pk_mul_f32 v[140:141], v[140:141], v[172:173]
	v_pk_mul_f32 v[136:137], v[136:137], v[168:169]
	v_pk_mul_f32 v[132:133], v[132:133], v[164:165]
	v_pk_mul_f32 v[128:129], v[128:129], v[160:161]
	v_pk_mul_f32 v[126:127], v[126:127], v[174:175]
	v_pk_mul_f32 v[122:123], v[122:123], v[170:171]
	v_pk_mul_f32 v[118:119], v[118:119], v[166:167]
	v_pk_mul_f32 v[114:115], v[114:115], v[162:163]
	v_pk_mul_f32 v[124:125], v[124:125], v[172:173]
	v_pk_mul_f32 v[120:121], v[120:121], v[168:169]
	v_pk_mul_f32 v[116:117], v[116:117], v[164:165]
	v_pk_mul_f32 v[112:113], v[112:113], v[160:161]
	v_pk_mul_f32 v[78:79], v[78:79], v[174:175]
	v_pk_mul_f32 v[74:75], v[74:75], v[170:171]
	v_pk_mul_f32 v[70:71], v[70:71], v[166:167]
	v_pk_mul_f32 v[66:67], v[66:67], v[162:163]
	v_pk_mul_f32 v[76:77], v[76:77], v[172:173]
	v_pk_mul_f32 v[72:73], v[72:73], v[168:169]
	v_pk_mul_f32 v[68:69], v[68:69], v[164:165]
	v_pk_mul_f32 v[64:65], v[64:65], v[160:161]
	v_pk_mul_f32 v[46:47], v[46:47], v[174:175]
	v_pk_mul_f32 v[42:43], v[42:43], v[170:171]
	v_pk_mul_f32 v[38:39], v[38:39], v[166:167]
	v_pk_mul_f32 v[34:35], v[34:35], v[162:163]
	v_pk_mul_f32 v[44:45], v[44:45], v[172:173]
	v_pk_mul_f32 v[40:41], v[40:41], v[168:169]
	v_pk_mul_f32 v[36:37], v[36:37], v[164:165]
	v_pk_mul_f32 v[32:33], v[32:33], v[160:161]
	v_pk_mul_f32 v[110:111], v[110:111], v[158:159]
	v_pk_mul_f32 v[106:107], v[106:107], v[154:155]
	v_pk_mul_f32 v[102:103], v[102:103], v[150:151]
	v_pk_mul_f32 v[98:99], v[98:99], v[146:147]
	v_pk_mul_f32 v[108:109], v[108:109], v[156:157]
	v_pk_mul_f32 v[104:105], v[104:105], v[152:153]
	v_pk_mul_f32 v[100:101], v[100:101], v[148:149]
	v_pk_mul_f32 v[96:97], v[96:97], v[144:145]
	v_pk_mul_f32 v[94:95], v[94:95], v[158:159]
	v_pk_mul_f32 v[90:91], v[90:91], v[154:155]
	v_pk_mul_f32 v[86:87], v[86:87], v[150:151]
	v_pk_mul_f32 v[82:83], v[82:83], v[146:147]
	v_pk_mul_f32 v[92:93], v[92:93], v[156:157]
	v_pk_mul_f32 v[88:89], v[88:89], v[152:153]
	v_pk_mul_f32 v[84:85], v[84:85], v[148:149]
	v_pk_mul_f32 v[80:81], v[80:81], v[144:145]
	v_pk_mul_f32 v[62:63], v[62:63], v[158:159]
	v_pk_mul_f32 v[58:59], v[58:59], v[154:155]
	v_pk_mul_f32 v[54:55], v[54:55], v[150:151]
	v_pk_mul_f32 v[50:51], v[50:51], v[146:147]
	v_pk_mul_f32 v[60:61], v[60:61], v[156:157]
	v_pk_mul_f32 v[56:57], v[56:57], v[152:153]
	v_pk_mul_f32 v[52:53], v[52:53], v[148:149]
	v_pk_mul_f32 v[48:49], v[48:49], v[144:145]
	v_pk_mul_f32 v[30:31], v[30:31], v[158:159]
	v_pk_mul_f32 v[26:27], v[26:27], v[154:155]
	v_pk_mul_f32 v[22:23], v[22:23], v[150:151]
	v_pk_mul_f32 v[18:19], v[18:19], v[146:147]
	v_pk_mul_f32 v[28:29], v[28:29], v[156:157]
	v_pk_mul_f32 v[24:25], v[24:25], v[152:153]
	v_pk_mul_f32 v[20:21], v[20:21], v[148:149]
	v_pk_mul_f32 v[16:17], v[16:17], v[144:145]
	s_branch .LBB0_1267

.LBB0_1280:
	s_and_saveexec_b64 s[0:1], s[8:9]
	ds_write2_b32 v235, v243, v244 offset1:32
	s_or_b64 exec, exec, s[0:1]
	s_waitcnt lgkmcnt(0)
	ds_read_b128 v[160:163], v236
	ds_read_b128 v[164:167], v236 offset:32
	ds_read_b128 v[168:171], v236 offset:64
	ds_read_b128 v[172:175], v236 offset:96
	ds_read_b128 v[144:147], v236 offset:128
	ds_read_b128 v[148:151], v236 offset:160
	ds_read_b128 v[152:155], v236 offset:192
	ds_read_b128 v[156:159], v236 offset:224
	s_waitcnt lgkmcnt(0)
	v_pk_mul_f32 v[142:143], v[142:143], v[174:175]
	v_pk_mul_f32 v[138:139], v[138:139], v[170:171]
	v_pk_mul_f32 v[134:135], v[134:135], v[166:167]
	v_pk_mul_f32 v[130:131], v[130:131], v[162:163]
	v_pk_mul_f32 v[140:141], v[140:141], v[172:173]
	v_pk_mul_f32 v[136:137], v[136:137], v[168:169]
	v_pk_mul_f32 v[132:133], v[132:133], v[164:165]
	v_pk_mul_f32 v[128:129], v[128:129], v[160:161]
	v_pk_mul_f32 v[126:127], v[126:127], v[174:175]
	v_pk_mul_f32 v[122:123], v[122:123], v[170:171]
	v_pk_mul_f32 v[118:119], v[118:119], v[166:167]
	v_pk_mul_f32 v[114:115], v[114:115], v[162:163]
	v_pk_mul_f32 v[124:125], v[124:125], v[172:173]
	v_pk_mul_f32 v[120:121], v[120:121], v[168:169]
	v_pk_mul_f32 v[116:117], v[116:117], v[164:165]
	v_pk_mul_f32 v[112:113], v[112:113], v[160:161]
	v_pk_mul_f32 v[78:79], v[78:79], v[174:175]
	v_pk_mul_f32 v[74:75], v[74:75], v[170:171]
	v_pk_mul_f32 v[70:71], v[70:71], v[166:167]
	v_pk_mul_f32 v[66:67], v[66:67], v[162:163]
	v_pk_mul_f32 v[76:77], v[76:77], v[172:173]
	v_pk_mul_f32 v[72:73], v[72:73], v[168:169]
	v_pk_mul_f32 v[68:69], v[68:69], v[164:165]
	v_pk_mul_f32 v[64:65], v[64:65], v[160:161]
	v_pk_mul_f32 v[46:47], v[46:47], v[174:175]
	v_pk_mul_f32 v[42:43], v[42:43], v[170:171]
	v_pk_mul_f32 v[38:39], v[38:39], v[166:167]
	v_pk_mul_f32 v[34:35], v[34:35], v[162:163]
	v_pk_mul_f32 v[44:45], v[44:45], v[172:173]
	v_pk_mul_f32 v[40:41], v[40:41], v[168:169]
	v_pk_mul_f32 v[36:37], v[36:37], v[164:165]
	v_pk_mul_f32 v[32:33], v[32:33], v[160:161]
	v_pk_mul_f32 v[110:111], v[110:111], v[158:159]
	v_pk_mul_f32 v[106:107], v[106:107], v[154:155]
	v_pk_mul_f32 v[102:103], v[102:103], v[150:151]
	v_pk_mul_f32 v[98:99], v[98:99], v[146:147]
	v_pk_mul_f32 v[108:109], v[108:109], v[156:157]
	v_pk_mul_f32 v[104:105], v[104:105], v[152:153]
	v_pk_mul_f32 v[100:101], v[100:101], v[148:149]
	v_pk_mul_f32 v[96:97], v[96:97], v[144:145]
	v_pk_mul_f32 v[94:95], v[94:95], v[158:159]
	v_pk_mul_f32 v[90:91], v[90:91], v[154:155]
	v_pk_mul_f32 v[86:87], v[86:87], v[150:151]
	v_pk_mul_f32 v[82:83], v[82:83], v[146:147]
	v_pk_mul_f32 v[92:93], v[92:93], v[156:157]
	v_pk_mul_f32 v[88:89], v[88:89], v[152:153]
	v_pk_mul_f32 v[84:85], v[84:85], v[148:149]
	v_pk_mul_f32 v[80:81], v[80:81], v[144:145]
	v_pk_mul_f32 v[62:63], v[62:63], v[158:159]
	v_pk_mul_f32 v[58:59], v[58:59], v[154:155]
	v_pk_mul_f32 v[54:55], v[54:55], v[150:151]
	v_pk_mul_f32 v[50:51], v[50:51], v[146:147]
	v_pk_mul_f32 v[60:61], v[60:61], v[156:157]
	v_pk_mul_f32 v[56:57], v[56:57], v[152:153]
	v_pk_mul_f32 v[52:53], v[52:53], v[148:149]
	v_pk_mul_f32 v[48:49], v[48:49], v[144:145]
	v_pk_mul_f32 v[30:31], v[30:31], v[158:159]
	v_pk_mul_f32 v[26:27], v[26:27], v[154:155]
	v_pk_mul_f32 v[22:23], v[22:23], v[150:151]
	v_pk_mul_f32 v[18:19], v[18:19], v[146:147]
	v_pk_mul_f32 v[28:29], v[28:29], v[156:157]
	v_pk_mul_f32 v[24:25], v[24:25], v[152:153]
	v_pk_mul_f32 v[20:21], v[20:21], v[148:149]
	v_pk_mul_f32 v[16:17], v[16:17], v[144:145]
	s_branch .LBB0_1283

.LBB0_2097:
	s_cmpk_gt_u32 s69, 0xfe
	s_cbranch_scc1 .Lv0_c2
	s_waitcnt vmcnt(4)

.LBB0_2103:
.Lfz1_c2:
	s_and_b32 s27, s68, 0xc000
	v_add_u32_e32 v241, s27, v233
	ds_read_b128 v[144:147], v241 offset:0
	v_xor_b32_e32 v240, 32, v241
	ds_read_b128 v[148:151], v240 offset:0
	v_xor_b32_e32 v239, 64, v241
	ds_read_b128 v[152:155], v239 offset:0
	v_xor_b32_e32 v0, 0x60, v241
	ds_read_b128 v[156:159], v0 offset:0
	s_waitcnt lgkmcnt(0)
	v_mfma_f32_32x32x16_bf16 v[212:227], v[144:147], v[176:179], 0
	v_mfma_f32_32x32x16_bf16 v[212:227], v[148:151], v[180:183], v[212:227]
	v_mfma_f32_32x32x16_bf16 v[212:227], v[152:155], v[184:187], v[212:227]
	v_mfma_f32_32x32x16_bf16 v[212:227], v[156:159], v[188:191], v[212:227]
	ds_read_b128 v[144:147], v241 offset:0x80
	ds_read_b128 v[148:151], v240 offset:0x80
	ds_read_b128 v[152:155], v239 offset:0x80
	ds_read_b128 v[156:159], v0 offset:0x80
	v_cmp_eq_f32_e32 vcc, 0, v238
	v_cmp_eq_f32_e64 s[6:7], 0, v237
	s_and_b64 s[0:1], vcc, s[6:7]
	s_cmp_eq_u64 s[0:1], exec
	s_waitcnt lgkmcnt(0)
	v_mfma_f32_32x32x16_bf16 v[160:175], v[144:147], v[192:195], 0
	v_mfma_f32_32x32x16_bf16 v[160:175], v[148:151], v[196:199], v[160:175]
	v_mfma_f32_32x32x16_bf16 v[160:175], v[152:155], v[200:203], v[160:175]
	v_mfma_f32_32x32x16_bf16 v[160:175], v[156:159], v[204:207], v[160:175]
	s_cbranch_scc0 .LBB0_2105
	v_exp_f32_e32 v144, v212
	v_exp_f32_e32 v145, v213
	v_exp_f32_e32 v146, v214
	v_exp_f32_e32 v147, v215
	v_exp_f32_e32 v148, v216
	v_exp_f32_e32 v149, v217
	v_exp_f32_e32 v150, v218
	v_exp_f32_e32 v151, v219
	v_exp_f32_e32 v152, v220
	v_exp_f32_e32 v153, v221
	v_exp_f32_e32 v154, v222
	v_exp_f32_e32 v155, v223
	v_exp_f32_e32 v156, v224
	v_exp_f32_e32 v157, v225
	v_exp_f32_e32 v158, v226
	v_exp_f32_e32 v159, v227
	v_add_f32_e32 v252, v144, v145
	v_add_f32_e32 v253, v146, v147
	v_add_f32_e32 v254, v148, v149
	v_add_f32_e32 v255, v150, v151
	v_add_f32_e32 v252, v252, v152
	v_add_f32_e32 v253, v253, v153
	v_add_f32_e32 v254, v254, v154
	v_add_f32_e32 v255, v255, v155
	v_add_f32_e32 v252, v252, v156
	v_add_f32_e32 v253, v253, v157
	v_add_f32_e32 v254, v254, v158
	v_add_f32_e32 v255, v255, v159
	v_cvt_pk_bf16_f32 v216, v144, v145
	v_cvt_pk_bf16_f32 v217, v146, v147
	v_add_f32_e32 v252, v252, v253
	v_add_f32_e32 v254, v254, v255
	v_cvt_pk_bf16_f32 v218, v148, v149
	v_cvt_pk_bf16_f32 v219, v150, v151
	v_cvt_pk_bf16_f32 v224, v152, v153
	v_add_f32_e32 v252, v252, v254
	v_cvt_pk_bf16_f32 v225, v154, v155
	v_cvt_pk_bf16_f32 v226, v156, v157
	v_cvt_pk_bf16_f32 v227, v158, v159
	v_add_u32_e32 v253, 0xde801b54, v252
	v_cmp_gt_u32_e32 vcc, 0x3bff7543, v253
	s_cmp_lg_u64 vcc, exec
	s_cbranch_scc1 .LBB0_2140
	v_add_f32_e32 v15, v15, v252
	v_exp_f32_e32 v144, v160
	v_exp_f32_e32 v145, v161
	v_exp_f32_e32 v146, v162
	v_exp_f32_e32 v147, v163
	v_exp_f32_e32 v148, v164
	v_exp_f32_e32 v149, v165
	v_exp_f32_e32 v150, v166
	v_exp_f32_e32 v151, v167
	v_exp_f32_e32 v152, v168
	v_exp_f32_e32 v153, v169
	v_exp_f32_e32 v154, v170
	v_exp_f32_e32 v155, v171
	v_exp_f32_e32 v156, v172
	v_exp_f32_e32 v157, v173
	v_exp_f32_e32 v158, v174
	v_exp_f32_e32 v159, v175
	v_add_f32_e32 v252, v144, v145
	v_add_f32_e32 v253, v146, v147
	v_add_f32_e32 v254, v148, v149
	v_add_f32_e32 v255, v150, v151
	v_add_f32_e32 v252, v252, v152
	v_add_f32_e32 v253, v253, v153
	v_add_f32_e32 v254, v254, v154
	v_add_f32_e32 v255, v255, v155
	v_add_f32_e32 v252, v252, v156
	v_add_f32_e32 v253, v253, v157
	v_add_f32_e32 v254, v254, v158
	v_add_f32_e32 v255, v255, v159
	v_cvt_pk_bf16_f32 v212, v144, v145
	v_cvt_pk_bf16_f32 v213, v146, v147
	v_add_f32_e32 v252, v252, v253
	v_add_f32_e32 v254, v254, v255
	v_cvt_pk_bf16_f32 v214, v148, v149
	v_cvt_pk_bf16_f32 v215, v150, v151
	v_cvt_pk_bf16_f32 v220, v152, v153
	v_add_f32_e32 v252, v252, v254
	v_cvt_pk_bf16_f32 v221, v154, v155
	v_cvt_pk_bf16_f32 v222, v156, v157
	v_cvt_pk_bf16_f32 v223, v158, v159
	v_add_u32_e32 v253, 0xde801b54, v252
	v_cmp_gt_u32_e32 vcc, 0x3bff7543, v253
	s_cmp_lg_u64 vcc, exec
	s_cbranch_scc1 .Lfzsb1_c2
	v_add_f32_e32 v14, v14, v252
.LBB0_2121:
	v_add_u32_e32 v242, s27, v234
	ds_read_b64_tr_b16 v[160:161], v242 offset:0x0
	ds_read_b64_tr_b16 v[162:163], v242 offset:0x100
	ds_read_b64_tr_b16 v[164:165], v242 offset:0x1000
	ds_read_b64_tr_b16 v[166:167], v242 offset:0x1100
	s_waitcnt lgkmcnt(2)
	v_mfma_f32_32x32x16_bf16 v[128:143], v[216:219], v[160:163], v[128:143]
	ds_read_b64_tr_b16 v[168:169], v242 offset:0x200
	v_mfma_f32_32x32x16_bf16 v[96:111], v[212:215], v[160:163], v[96:111]
	ds_read_b64_tr_b16 v[170:171], v242 offset:0x300
	s_waitcnt lgkmcnt(2)
	v_mfma_f32_32x32x16_bf16 v[128:143], v[224:227], v[164:167], v[128:143]
	ds_read_b64_tr_b16 v[172:173], v242 offset:0x1200
	v_mfma_f32_32x32x16_bf16 v[96:111], v[220:223], v[164:167], v[96:111]
	ds_read_b64_tr_b16 v[174:175], v242 offset:0x1300
	s_waitcnt lgkmcnt(2)
	v_mfma_f32_32x32x16_bf16 v[112:127], v[216:219], v[168:171], v[112:127]
	ds_read_b64_tr_b16 v[160:161], v242 offset:0x400
	v_mfma_f32_32x32x16_bf16 v[80:95], v[212:215], v[168:171], v[80:95]
	ds_read_b64_tr_b16 v[162:163], v242 offset:0x500
	s_waitcnt lgkmcnt(2)
	v_mfma_f32_32x32x16_bf16 v[112:127], v[224:227], v[172:175], v[112:127]
	ds_read_b64_tr_b16 v[164:165], v242 offset:0x1400
	v_mfma_f32_32x32x16_bf16 v[80:95], v[220:223], v[172:175], v[80:95]
	ds_read_b64_tr_b16 v[166:167], v242 offset:0x1500
	ds_read_b128 v[144:147], v241 offset:0x2000
	ds_read_b128 v[148:151], v240 offset:0x2000
	ds_read_b128 v[156:159], v239 offset:0x2000
	ds_read_b128 v[244:247], v0 offset:0x2000
	s_waitcnt lgkmcnt(6)
	v_mfma_f32_32x32x16_bf16 v[64:79], v[216:219], v[160:163], v[64:79]
	ds_read_b64_tr_b16 v[168:169], v242 offset:0x600
	v_mfma_f32_32x32x16_bf16 v[32:47], v[212:215], v[160:163], v[32:47]
	ds_read_b64_tr_b16 v[170:171], v242 offset:0x700
	s_waitcnt lgkmcnt(6)
	v_mfma_f32_32x32x16_bf16 v[64:79], v[224:227], v[164:167], v[64:79]
	ds_read_b64_tr_b16 v[172:173], v242 offset:0x1600
	v_mfma_f32_32x32x16_bf16 v[32:47], v[220:223], v[164:167], v[32:47]
	ds_read_b64_tr_b16 v[174:175], v242 offset:0x1700
	s_waitcnt lgkmcnt(2)
	v_mfma_f32_32x32x16_bf16 v[48:63], v[216:219], v[168:171], v[48:63]
	v_mfma_f32_32x32x16_bf16 v[16:31], v[212:215], v[168:171], v[16:31]
	s_waitcnt lgkmcnt(0)
	v_mfma_f32_32x32x16_bf16 v[48:63], v[224:227], v[172:175], v[48:63]
	v_mfma_f32_32x32x16_bf16 v[16:31], v[220:223], v[172:175], v[16:31]
	s_waitcnt lgkmcnt(0)
	v_mfma_f32_32x32x16_bf16 v[212:227], v[144:147], v[176:179], 0
	v_mfma_f32_32x32x16_bf16 v[212:227], v[148:151], v[180:183], v[212:227]
	v_mfma_f32_32x32x16_bf16 v[212:227], v[156:159], v[184:187], v[212:227]
	v_mfma_f32_32x32x16_bf16 v[212:227], v[244:247], v[188:191], v[212:227]
	ds_read_b128 v[144:147], v241 offset:0x2080
	ds_read_b128 v[148:151], v240 offset:0x2080
	ds_read_b128 v[152:155], v239 offset:0x2080
	ds_read_b128 v[156:159], v0 offset:0x2080
	v_cmp_eq_f32_e32 vcc, 0, v238
	v_cmp_eq_f32_e64 s[6:7], 0, v237
	s_and_b64 s[0:1], vcc, s[6:7]
	s_cmp_eq_u64 s[0:1], exec
	s_waitcnt lgkmcnt(0)
	v_mfma_f32_32x32x16_bf16 v[160:175], v[144:147], v[192:195], 0
	v_mfma_f32_32x32x16_bf16 v[160:175], v[148:151], v[196:199], v[160:175]
	v_mfma_f32_32x32x16_bf16 v[160:175], v[152:155], v[200:203], v[160:175]
	v_mfma_f32_32x32x16_bf16 v[160:175], v[156:159], v[204:207], v[160:175]
	s_cbranch_scc0 .Lfz2o_c2
	v_exp_f32_e32 v144, v212
	v_exp_f32_e32 v145, v213
	v_exp_f32_e32 v146, v214
	v_exp_f32_e32 v147, v215
	v_exp_f32_e32 v148, v216
	v_exp_f32_e32 v149, v217
	v_exp_f32_e32 v150, v218
	v_exp_f32_e32 v151, v219
	v_exp_f32_e32 v152, v220
	v_exp_f32_e32 v153, v221
	v_exp_f32_e32 v154, v222
	v_exp_f32_e32 v155, v223
	v_exp_f32_e32 v156, v224
	v_exp_f32_e32 v157, v225
	v_exp_f32_e32 v158, v226
	v_exp_f32_e32 v159, v227
	v_add_f32_e32 v252, v144, v145
	v_add_f32_e32 v253, v146, v147
	v_add_f32_e32 v254, v148, v149
	v_add_f32_e32 v255, v150, v151
	v_add_f32_e32 v252, v252, v152
	v_add_f32_e32 v253, v253, v153
	v_add_f32_e32 v254, v254, v154
	v_add_f32_e32 v255, v255, v155
	v_add_f32_e32 v252, v252, v156
	v_add_f32_e32 v253, v253, v157
	v_add_f32_e32 v254, v254, v158
	v_add_f32_e32 v255, v255, v159
	v_cvt_pk_bf16_f32 v6, v144, v145
	v_cvt_pk_bf16_f32 v7, v146, v147
	v_add_f32_e32 v252, v252, v253
	v_add_f32_e32 v254, v254, v255
	v_cvt_pk_bf16_f32 v8, v148, v149
	v_cvt_pk_bf16_f32 v9, v150, v151
	v_cvt_pk_bf16_f32 v208, v152, v153
	v_add_f32_e32 v252, v252, v254
	v_cvt_pk_bf16_f32 v209, v154, v155
	v_cvt_pk_bf16_f32 v210, v156, v157
	v_cvt_pk_bf16_f32 v211, v158, v159
	v_add_u32_e32 v253, 0xde801b54, v252
	v_cmp_gt_u32_e32 vcc, 0x3bff7543, v253
	s_cmp_lg_u64 vcc, exec
	s_cbranch_scc1 .LBB0_2152
	v_add_f32_e32 v15, v15, v252
	v_exp_f32_e32 v144, v160
	v_exp_f32_e32 v145, v161
	v_exp_f32_e32 v146, v162
	v_exp_f32_e32 v147, v163
	v_exp_f32_e32 v148, v164
	v_exp_f32_e32 v149, v165
	v_exp_f32_e32 v150, v166
	v_exp_f32_e32 v151, v167
	v_exp_f32_e32 v152, v168
	v_exp_f32_e32 v153, v169
	v_exp_f32_e32 v154, v170
	v_exp_f32_e32 v155, v171
	v_exp_f32_e32 v156, v172
	v_exp_f32_e32 v157, v173
	v_exp_f32_e32 v158, v174
	v_exp_f32_e32 v159, v175
	v_add_f32_e32 v252, v144, v145
	v_add_f32_e32 v253, v146, v147
	v_add_f32_e32 v254, v148, v149
	v_add_f32_e32 v255, v150, v151
	v_add_f32_e32 v252, v252, v152
	v_add_f32_e32 v253, v253, v153
	v_add_f32_e32 v254, v254, v154
	v_add_f32_e32 v255, v255, v155
	v_add_f32_e32 v252, v252, v156
	v_add_f32_e32 v253, v253, v157
	v_add_f32_e32 v254, v254, v158
	v_add_f32_e32 v255, v255, v159
	v_cvt_pk_bf16_f32 v2, v144, v145
	v_cvt_pk_bf16_f32 v3, v146, v147
	v_add_f32_e32 v252, v252, v253
	v_add_f32_e32 v254, v254, v255
	v_cvt_pk_bf16_f32 v4, v148, v149
	v_cvt_pk_bf16_f32 v5, v150, v151
	v_cvt_pk_bf16_f32 v10, v152, v153
	v_add_f32_e32 v252, v252, v254
	v_cvt_pk_bf16_f32 v11, v154, v155
	v_cvt_pk_bf16_f32 v12, v156, v157
	v_cvt_pk_bf16_f32 v13, v158, v159
	v_add_u32_e32 v253, 0xde801b54, v252
	v_cmp_gt_u32_e32 vcc, 0x3bff7543, v253
	s_cmp_lg_u64 vcc, exec
	s_cbranch_scc1 .Lfzsb2_c2
	v_add_f32_e32 v14, v14, v252

.LBB0_2118:
	s_and_saveexec_b64 s[0:1], s[4:5]
	ds_write2_b32 v235, v242, v243 offset1:32
	s_or_b64 exec, exec, s[0:1]
	s_waitcnt lgkmcnt(0)
	ds_read_b128 v[160:163], v236
	ds_read_b128 v[164:167], v236 offset:32
	ds_read_b128 v[168:171], v236 offset:64
	ds_read_b128 v[172:175], v236 offset:96
	ds_read_b128 v[144:147], v236 offset:128
	ds_read_b128 v[148:151], v236 offset:160
	ds_read_b128 v[152:155], v236 offset:192
	ds_read_b128 v[156:159], v236 offset:224
	s_waitcnt lgkmcnt(0)
	v_pk_mul_f32 v[142:143], v[142:143], v[174:175]
	v_pk_mul_f32 v[138:139], v[138:139], v[170:171]
	v_pk_mul_f32 v[134:135], v[134:135], v[166:167]
	v_pk_mul_f32 v[130:131], v[130:131], v[162:163]
	v_pk_mul_f32 v[140:141], v[140:141], v[172:173]
	v_pk_mul_f32 v[136:137], v[136:137], v[168:169]
	v_pk_mul_f32 v[132:133], v[132:133], v[164:165]
	v_pk_mul_f32 v[128:129], v[128:129], v[160:161]
	v_pk_mul_f32 v[126:127], v[126:127], v[174:175]
	v_pk_mul_f32 v[122:123], v[122:123], v[170:171]
	v_pk_mul_f32 v[118:119], v[118:119], v[166:167]
	v_pk_mul_f32 v[114:115], v[114:115], v[162:163]
	v_pk_mul_f32 v[124:125], v[124:125], v[172:173]
	v_pk_mul_f32 v[120:121], v[120:121], v[168:169]
	v_pk_mul_f32 v[116:117], v[116:117], v[164:165]
	v_pk_mul_f32 v[112:113], v[112:113], v[160:161]
	v_pk_mul_f32 v[78:79], v[78:79], v[174:175]
	v_pk_mul_f32 v[74:75], v[74:75], v[170:171]
	v_pk_mul_f32 v[70:71], v[70:71], v[166:167]
	v_pk_mul_f32 v[66:67], v[66:67], v[162:163]
	v_pk_mul_f32 v[76:77], v[76:77], v[172:173]
	v_pk_mul_f32 v[72:73], v[72:73], v[168:169]
	v_pk_mul_f32 v[68:69], v[68:69], v[164:165]
	v_pk_mul_f32 v[64:65], v[64:65], v[160:161]
	v_pk_mul_f32 v[62:63], v[62:63], v[174:175]
	v_pk_mul_f32 v[58:59], v[58:59], v[170:171]
	v_pk_mul_f32 v[54:55], v[54:55], v[166:167]
	v_pk_mul_f32 v[50:51], v[50:51], v[162:163]
	v_pk_mul_f32 v[60:61], v[60:61], v[172:173]
	v_pk_mul_f32 v[56:57], v[56:57], v[168:169]
	v_pk_mul_f32 v[52:53], v[52:53], v[164:165]
	v_pk_mul_f32 v[48:49], v[48:49], v[160:161]
	v_pk_mul_f32 v[110:111], v[110:111], v[158:159]
	v_pk_mul_f32 v[106:107], v[106:107], v[154:155]
	v_pk_mul_f32 v[102:103], v[102:103], v[150:151]
	v_pk_mul_f32 v[98:99], v[98:99], v[146:147]
	v_pk_mul_f32 v[108:109], v[108:109], v[156:157]
	v_pk_mul_f32 v[104:105], v[104:105], v[152:153]
	v_pk_mul_f32 v[100:101], v[100:101], v[148:149]
	v_pk_mul_f32 v[96:97], v[96:97], v[144:145]
	v_pk_mul_f32 v[94:95], v[94:95], v[158:159]
	v_pk_mul_f32 v[90:91], v[90:91], v[154:155]
	v_pk_mul_f32 v[86:87], v[86:87], v[150:151]
	v_pk_mul_f32 v[82:83], v[82:83], v[146:147]
	v_pk_mul_f32 v[92:93], v[92:93], v[156:157]
	v_pk_mul_f32 v[88:89], v[88:89], v[152:153]
	v_pk_mul_f32 v[84:85], v[84:85], v[148:149]
	v_pk_mul_f32 v[80:81], v[80:81], v[144:145]
	v_pk_mul_f32 v[46:47], v[46:47], v[158:159]
	v_pk_mul_f32 v[42:43], v[42:43], v[154:155]
	v_pk_mul_f32 v[38:39], v[38:39], v[150:151]
	v_pk_mul_f32 v[34:35], v[34:35], v[146:147]
	v_pk_mul_f32 v[44:45], v[44:45], v[156:157]
	v_pk_mul_f32 v[40:41], v[40:41], v[152:153]
	v_pk_mul_f32 v[36:37], v[36:37], v[148:149]
	v_pk_mul_f32 v[32:33], v[32:33], v[144:145]
	v_pk_mul_f32 v[30:31], v[30:31], v[158:159]
	v_pk_mul_f32 v[26:27], v[26:27], v[154:155]
	v_pk_mul_f32 v[22:23], v[22:23], v[150:151]
	v_pk_mul_f32 v[18:19], v[18:19], v[146:147]
	v_pk_mul_f32 v[28:29], v[28:29], v[156:157]
	v_pk_mul_f32 v[24:25], v[24:25], v[152:153]
	v_pk_mul_f32 v[20:21], v[20:21], v[148:149]
	v_pk_mul_f32 v[16:17], v[16:17], v[144:145]
	s_branch .LBB0_2121

.LBB0_2134:
	s_and_saveexec_b64 s[0:1], s[4:5]
	ds_write2_b32 v235, v243, v244 offset1:32
	s_or_b64 exec, exec, s[0:1]
	s_waitcnt lgkmcnt(0)
	ds_read_b128 v[160:163], v236
	ds_read_b128 v[164:167], v236 offset:32
	ds_read_b128 v[168:171], v236 offset:64
	ds_read_b128 v[172:175], v236 offset:96
	ds_read_b128 v[144:147], v236 offset:128
	ds_read_b128 v[148:151], v236 offset:160
	ds_read_b128 v[152:155], v236 offset:192
	ds_read_b128 v[156:159], v236 offset:224
	s_waitcnt lgkmcnt(0)
	v_pk_mul_f32 v[142:143], v[142:143], v[174:175]
	v_pk_mul_f32 v[138:139], v[138:139], v[170:171]
	v_pk_mul_f32 v[134:135], v[134:135], v[166:167]
	v_pk_mul_f32 v[130:131], v[130:131], v[162:163]
	v_pk_mul_f32 v[140:141], v[140:141], v[172:173]
	v_pk_mul_f32 v[136:137], v[136:137], v[168:169]
	v_pk_mul_f32 v[132:133], v[132:133], v[164:165]
	v_pk_mul_f32 v[128:129], v[128:129], v[160:161]
	v_pk_mul_f32 v[126:127], v[126:127], v[174:175]
	v_pk_mul_f32 v[122:123], v[122:123], v[170:171]
	v_pk_mul_f32 v[118:119], v[118:119], v[166:167]
	v_pk_mul_f32 v[114:115], v[114:115], v[162:163]
	v_pk_mul_f32 v[124:125], v[124:125], v[172:173]
	v_pk_mul_f32 v[120:121], v[120:121], v[168:169]
	v_pk_mul_f32 v[116:117], v[116:117], v[164:165]
	v_pk_mul_f32 v[112:113], v[112:113], v[160:161]
	v_pk_mul_f32 v[78:79], v[78:79], v[174:175]
	v_pk_mul_f32 v[74:75], v[74:75], v[170:171]
	v_pk_mul_f32 v[70:71], v[70:71], v[166:167]
	v_pk_mul_f32 v[66:67], v[66:67], v[162:163]
	v_pk_mul_f32 v[76:77], v[76:77], v[172:173]
	v_pk_mul_f32 v[72:73], v[72:73], v[168:169]
	v_pk_mul_f32 v[68:69], v[68:69], v[164:165]
	v_pk_mul_f32 v[64:65], v[64:65], v[160:161]
	v_pk_mul_f32 v[62:63], v[62:63], v[174:175]
	v_pk_mul_f32 v[58:59], v[58:59], v[170:171]
	v_pk_mul_f32 v[54:55], v[54:55], v[166:167]
	v_pk_mul_f32 v[50:51], v[50:51], v[162:163]
	v_pk_mul_f32 v[60:61], v[60:61], v[172:173]
	v_pk_mul_f32 v[56:57], v[56:57], v[168:169]
	v_pk_mul_f32 v[52:53], v[52:53], v[164:165]
	v_pk_mul_f32 v[48:49], v[48:49], v[160:161]
	v_pk_mul_f32 v[110:111], v[110:111], v[158:159]
	v_pk_mul_f32 v[106:107], v[106:107], v[154:155]
	v_pk_mul_f32 v[102:103], v[102:103], v[150:151]
	v_pk_mul_f32 v[98:99], v[98:99], v[146:147]
	v_pk_mul_f32 v[108:109], v[108:109], v[156:157]
	v_pk_mul_f32 v[104:105], v[104:105], v[152:153]
	v_pk_mul_f32 v[100:101], v[100:101], v[148:149]
	v_pk_mul_f32 v[96:97], v[96:97], v[144:145]
	v_pk_mul_f32 v[94:95], v[94:95], v[158:159]
	v_pk_mul_f32 v[90:91], v[90:91], v[154:155]
	v_pk_mul_f32 v[86:87], v[86:87], v[150:151]
	v_pk_mul_f32 v[82:83], v[82:83], v[146:147]
	v_pk_mul_f32 v[92:93], v[92:93], v[156:157]
	v_pk_mul_f32 v[88:89], v[88:89], v[152:153]
	v_pk_mul_f32 v[84:85], v[84:85], v[148:149]
	v_pk_mul_f32 v[80:81], v[80:81], v[144:145]
	v_pk_mul_f32 v[46:47], v[46:47], v[158:159]
	v_pk_mul_f32 v[42:43], v[42:43], v[154:155]
	v_pk_mul_f32 v[38:39], v[38:39], v[150:151]
	v_pk_mul_f32 v[34:35], v[34:35], v[146:147]
	v_pk_mul_f32 v[44:45], v[44:45], v[156:157]
	v_pk_mul_f32 v[40:41], v[40:41], v[152:153]
	v_pk_mul_f32 v[36:37], v[36:37], v[148:149]
	v_pk_mul_f32 v[32:33], v[32:33], v[144:145]
	v_pk_mul_f32 v[30:31], v[30:31], v[158:159]
	v_pk_mul_f32 v[26:27], v[26:27], v[154:155]
	v_pk_mul_f32 v[22:23], v[22:23], v[150:151]
	v_pk_mul_f32 v[18:19], v[18:19], v[146:147]
	v_pk_mul_f32 v[28:29], v[28:29], v[156:157]
	v_pk_mul_f32 v[24:25], v[24:25], v[152:153]
	v_pk_mul_f32 v[20:21], v[20:21], v[148:149]
	v_pk_mul_f32 v[16:17], v[16:17], v[144:145]
	s_branch .LBB0_2137
